# census check after first grid sync: 8 counter loads issued together (was 8 serial load/wait rounds); on top of fox direct-exp/negated cumsum/pipelined reads + gemm saddr
# speedup vs baseline: 1.0075x; 1.0008x over previous
.LBB0_180:
	s_or_b64 exec, exec, s[0:1]
	s_cmpk_lg_i32 s3, 0x100
	s_mov_b64 s[0:1], 0
	s_barrier
	s_cbranch_scc1 .LBB0_190
	v_readlane_b32 s16, v250, 0
	v_readlane_b32 s17, v250, 1
	v_readlane_b32 s18, v250, 2
	v_readlane_b32 s19, v250, 3
	v_readlane_b32 s20, v250, 4
	v_readlane_b32 s21, v250, 5
	v_readlane_b32 s22, v250, 6
	v_readlane_b32 s23, v250, 7
	v_readlane_b32 s24, v250, 8
	v_readlane_b32 s25, v250, 9
	v_readlane_b32 s26, v250, 10
	v_readlane_b32 s27, v250, 11
	v_readlane_b32 s28, v250, 12
	v_readlane_b32 s29, v250, 13
	v_readlane_b32 s30, v250, 14
	v_readlane_b32 s31, v250, 15
	v_mov_b32_e32 v0, 0x2d3c4000
	s_nop 4
	global_load_dword v1, v0, s[30:31] offset:1312 sc1
	global_load_dword v2, v0, s[30:31] offset:1316 sc1
	global_load_dword v3, v0, s[30:31] offset:1320 sc1
	global_load_dword v4, v0, s[30:31] offset:1324 sc1
	global_load_dword v5, v0, s[30:31] offset:1328 sc1
	global_load_dword v6, v0, s[30:31] offset:1332 sc1
	global_load_dword v7, v0, s[30:31] offset:1336 sc1
	global_load_dword v8, v0, s[30:31] offset:1340 sc1
	s_waitcnt vmcnt(0)
	v_xor_b32_e32 v1, 32, v1
	v_xor_b32_e32 v2, 32, v2
	v_xor_b32_e32 v3, 32, v3
	v_xor_b32_e32 v4, 32, v4
	v_xor_b32_e32 v5, 32, v5
	v_xor_b32_e32 v6, 32, v6
	v_xor_b32_e32 v7, 32, v7
	v_xor_b32_e32 v8, 32, v8
	v_or3_b32 v1, v1, v2, v3
	v_or3_b32 v4, v4, v5, v6
	v_or3_b32 v1, v1, v4, v7
	v_or_b32_e32 v1, v1, v8
	s_nop 1
	v_readfirstlane_b32 s0, v1
	s_cmp_eq_u32 s0, 0
	s_cselect_b64 s[0:1], -1, 0
